# differential-attention fast loop: one LDS wait per pair of MFMA operands and tile loads issued inside the first half-step
# speedup vs baseline: 1.0118x; 1.0047x over previous
.LfA_iter:
	s_add_u32 s8, s98, 0x40000
	s_addc_u32 s9, s99, 0
	s_sub_u32 s18, s98, 0x80000
	s_subb_u32 s19, s99, 0
	s_sub_u32 s20, s98, 0x40000
	s_subb_u32 s21, s99, 0
	v_add_u32_e32 v1, s30, v233
	s_waitcnt lgkmcnt(2)
	v_mfma_f32_32x32x16_bf16 v[80:95], v[2:5], v[112:115], 0
	ds_read_b64_tr_b16 v[2:3], v245 offset:15360
	ds_read_b64_tr_b16 v[4:5], v245 offset:17920
	v_exp_f32_e32 v96, v96
	v_exp_f32_e32 v97, v97
	v_add_u32_e32 v14, s101, v14
	v_add_u32_e32 v15, s101, v15
	v_mfma_f32_32x32x16_bf16 v[64:79], v[156:159], v[148:151], v[64:79]
	ds_read_b64_tr_b16 v[156:157], v1 offset:0
	ds_read_b64_tr_b16 v[158:159], v1 offset:2560
	v_exp_f32_e32 v98, v98
	v_exp_f32_e32 v99, v99
	v_add_f32_e32 v228, v228, v96
	v_add_u32_e32 v235, s101, v235
	v_mfma_f32_32x32x16_bf16 v[80:95], v[6:9], v[116:119], v[80:95]
	ds_read_b64_tr_b16 v[6:7], v245 offset:15424
	ds_read_b64_tr_b16 v[8:9], v245 offset:17984
	v_exp_f32_e32 v100, v100
	v_exp_f32_e32 v101, v101
	v_add_f32_e32 v228, v228, v97
	v_add_u32_e32 v244, s101, v244
	global_load_dwordx4 v[128:131], v246, s[98:99] offset:1024
	global_load_dwordx4 v[132:135], v246, s[8:9] offset:1024
	v_mfma_f32_32x32x16_bf16 v[48:63], v[160:163], v[148:151], v[48:63]
	ds_read_b64_tr_b16 v[160:161], v1 offset:64
	ds_read_b64_tr_b16 v[162:163], v1 offset:2624
	v_exp_f32_e32 v102, v102
	v_exp_f32_e32 v103, v103
	v_add_f32_e32 v228, v228, v98
	v_add_f32_e32 v228, v228, v99
	s_waitcnt lgkmcnt(8)
	v_mfma_f32_32x32x16_bf16 v[80:95], v[10:13], v[120:123], v[80:95]
	ds_read_b64_tr_b16 v[10:11], v245 offset:15488
	ds_read_b64_tr_b16 v[12:13], v245 offset:18048
	v_exp_f32_e32 v104, v104
	v_exp_f32_e32 v105, v105
	v_add_f32_e32 v228, v228, v100
	v_add_f32_e32 v228, v228, v101
	v_mfma_f32_32x32x16_bf16 v[16:31], v[164:167], v[148:151], v[16:31]
	ds_read_b64_tr_b16 v[164:165], v1 offset:128
	ds_read_b64_tr_b16 v[166:167], v1 offset:2688
	v_exp_f32_e32 v106, v106
	v_exp_f32_e32 v107, v107
	v_add_f32_e32 v228, v228, v102
	v_add_f32_e32 v228, v228, v103
	global_load_dwordx4 v[136:139], v246, s[18:19] offset:2048
	global_load_dwordx4 v[140:143], v246, s[20:21] offset:2048
	s_add_u32 s98, s98, 0x80000
	s_addc_u32 s99, s99, 0
	v_mfma_f32_32x32x16_bf16 v[80:95], v[152:155], v[124:127], v[80:95]
	ds_read_b64_tr_b16 v[152:153], v245 offset:15552
	ds_read_b64_tr_b16 v[154:155], v245 offset:18112
	v_exp_f32_e32 v108, v108
	v_exp_f32_e32 v109, v109
	v_add_f32_e32 v228, v228, v104
	v_add_f32_e32 v228, v228, v105
	v_mfma_f32_32x32x16_bf16 v[32:47], v[168:171], v[148:151], v[32:47]
	ds_read_b64_tr_b16 v[168:169], v1 offset:192
	ds_read_b64_tr_b16 v[170:171], v1 offset:2752
	v_exp_f32_e32 v110, v110
	v_exp_f32_e32 v111, v111
	v_add_f32_e32 v228, v228, v106
	v_add_f32_e32 v228, v228, v107
	s_waitcnt lgkmcnt(10)
	v_mfma_f32_32x32x16_bf16 v[64:79], v[2:5], v[144:147], v[64:79]
	ds_read_b128 v[236:239], v14
	v_cvt_pk_bf16_f32 v148, v96, v97
	v_cvt_pk_bf16_f32 v149, v98, v99
	v_cvt_pk_bf16_f32 v150, v100, v101
	v_cvt_pk_bf16_f32 v151, v102, v103
	v_add_f32_e32 v228, v228, v108
	v_mfma_f32_32x32x16_bf16 v[48:63], v[6:9], v[144:147], v[48:63]
	ds_read_b128 v[240:243], v15
	v_add_f32_e32 v228, v228, v109
	v_add_f32_e32 v228, v228, v110
	v_add_f32_e32 v228, v228, v111
	s_waitcnt lgkmcnt(4)
	v_mfma_f32_32x32x16_bf16 v[16:31], v[10:13], v[144:147], v[16:31]
	ds_read_b128 v[248:251], v235
	v_mov_b32_e32 v245, v1
	v_mfma_f32_32x32x16_bf16 v[32:47], v[152:155], v[144:147], v[32:47]
	ds_read_b128 v[252:255], v244
	v_cvt_pk_bf16_f32 v144, v104, v105
	v_cvt_pk_bf16_f32 v145, v106, v107
	v_cvt_pk_bf16_f32 v146, v108, v109
	v_cvt_pk_bf16_f32 v147, v110, v111
	s_waitcnt lgkmcnt(2)
	v_mfma_f32_32x32x16_bf16 v[96:111], v[236:239], v[112:115], 0
	ds_read_b64_tr_b16 v[236:237], v245 offset:5120
	ds_read_b64_tr_b16 v[238:239], v245 offset:7680
	v_exp_f32_e32 v80, v80
	v_exp_f32_e32 v81, v81
	v_mfma_f32_32x32x16_bf16 v[64:79], v[156:159], v[148:151], v[64:79]
	ds_read_b64_tr_b16 v[156:157], v245 offset:10240
	ds_read_b64_tr_b16 v[158:159], v245 offset:12800
	v_exp_f32_e32 v82, v82
	v_exp_f32_e32 v83, v83
	v_add_f32_e32 v228, v228, v80
	v_mfma_f32_32x32x16_bf16 v[96:111], v[240:243], v[116:119], v[96:111]
	ds_read_b64_tr_b16 v[240:241], v245 offset:5184
	ds_read_b64_tr_b16 v[242:243], v245 offset:7744
	v_exp_f32_e32 v84, v84
	v_exp_f32_e32 v85, v85
	v_add_f32_e32 v228, v228, v81
	v_mfma_f32_32x32x16_bf16 v[48:63], v[160:163], v[148:151], v[48:63]
	ds_read_b64_tr_b16 v[160:161], v245 offset:10304
	ds_read_b64_tr_b16 v[162:163], v245 offset:12864
	v_exp_f32_e32 v86, v86
	v_exp_f32_e32 v87, v87
	v_add_f32_e32 v228, v228, v82
	v_add_f32_e32 v228, v228, v83
	s_waitcnt lgkmcnt(8)
	v_mfma_f32_32x32x16_bf16 v[96:111], v[248:251], v[120:123], v[96:111]
	ds_read_b64_tr_b16 v[248:249], v245 offset:5248
	ds_read_b64_tr_b16 v[250:251], v245 offset:7808
	v_exp_f32_e32 v88, v88
	v_exp_f32_e32 v89, v89
	v_add_f32_e32 v228, v228, v84
	v_add_f32_e32 v228, v228, v85
	v_mfma_f32_32x32x16_bf16 v[16:31], v[164:167], v[148:151], v[16:31]
	ds_read_b64_tr_b16 v[164:165], v245 offset:10368
	ds_read_b64_tr_b16 v[166:167], v245 offset:12928
	v_exp_f32_e32 v90, v90
	v_exp_f32_e32 v91, v91
	v_add_f32_e32 v228, v228, v86
	v_add_f32_e32 v228, v228, v87
	v_mfma_f32_32x32x16_bf16 v[96:111], v[252:255], v[124:127], v[96:111]
	ds_read_b64_tr_b16 v[252:253], v245 offset:5312
	ds_read_b64_tr_b16 v[254:255], v245 offset:7872
	v_exp_f32_e32 v92, v92
	v_exp_f32_e32 v93, v93
	v_add_f32_e32 v228, v228, v88
	v_add_f32_e32 v228, v228, v89
	v_mfma_f32_32x32x16_bf16 v[32:47], v[168:171], v[148:151], v[32:47]
	ds_read_b64_tr_b16 v[168:169], v245 offset:10432
	ds_read_b64_tr_b16 v[170:171], v245 offset:12992
	v_exp_f32_e32 v94, v94
	v_exp_f32_e32 v95, v95
	v_add_f32_e32 v228, v228, v90
	v_add_f32_e32 v228, v228, v91
	s_waitcnt lgkmcnt(10)
	v_mfma_f32_32x32x16_bf16 v[64:79], v[236:239], v[144:147], v[64:79]
	s_waitcnt vmcnt(0)
	v_add_u32_e32 v1, s25, v206
	ds_write_b128 v1, v[128:131]
	ds_write_b128 v1, v[132:135] offset:8192
	v_cvt_pk_bf16_f32 v148, v80, v81
	v_cvt_pk_bf16_f32 v149, v82, v83
	v_cvt_pk_bf16_f32 v150, v84, v85
	v_cvt_pk_bf16_f32 v151, v86, v87
	v_add_f32_e32 v228, v228, v92
	v_mfma_f32_32x32x16_bf16 v[48:63], v[240:243], v[144:147], v[48:63]
	v_add_u32_e32 v1, s27, v205
	ds_write_b128 v1, v[136:139] offset:16384
	ds_write_b128 v1, v[140:143] offset:26624
	v_add_f32_e32 v228, v228, v93
	v_add_f32_e32 v228, v228, v94
	v_add_f32_e32 v228, v228, v95
	s_waitcnt lgkmcnt(6)
	v_mfma_f32_32x32x16_bf16 v[16:31], v[248:251], v[144:147], v[16:31]
	ds_read_b128 v[2:5], v14 offset:8192
	ds_read_b128 v[6:9], v15 offset:8192
	v_mfma_f32_32x32x16_bf16 v[32:47], v[252:255], v[144:147], v[32:47]
	ds_read_b128 v[10:13], v235 offset:8192
	ds_read_b128 v[152:155], v244 offset:8192
	v_cvt_pk_bf16_f32 v144, v88, v89
	v_cvt_pk_bf16_f32 v145, v90, v91
	v_cvt_pk_bf16_f32 v146, v92, v93
	v_cvt_pk_bf16_f32 v147, v94, v95
	s_sub_i32 s101, s25, s27
	s_mov_b32 s6, s30
	s_mov_b32 s30, s27
	s_mov_b32 s27, s25
	s_mov_b32 s25, s6
	s_add_i32 s12, s12, 64
	s_add_i32 s24, s24, 2
	s_add_i32 s29, s29, 1
	s_waitcnt lgkmcnt(4)
	s_barrier
	s_cmp_lt_i32 s24, s100
	s_cbranch_scc0 .LfA_exit
	s_add_i32 s7, s29, 0xfe
	s_cmp_lt_u32 s7, s36
	s_cbranch_scc1 .LfA_iter
